# asel XCD-local map variant: four (b,h) at a time per XCD (smaller L2 working set for the gathered Q rows)
# baseline (speedup 1.0000x reference)
.LBB0_1247:
	s_mul_hi_i32 s0, s71, 0x84210843
	s_add_i32 s0, s0, s71
	s_lshr_b32 s1, s0, 31
	s_ashr_i32 s0, s0, 10
	s_add_i32 s1, s0, s1
	s_mul_i32 s0, s1, 0xfffff840
	s_add_i32 s34, s0, s71
	s_and_b32 s0, s34, 7
	s_mulk_i32 s0, 0xf8
	s_lshr_b32 s4, s34, 3
	s_cmp_ge_u32 s4, 0x7c
	s_cselect_b32 s5, 1, 0
	s_mul_i32 s14, s5, 0x7c
	s_sub_i32 s4, s4, s14
	s_and_b32 s14, s4, 3
	s_lshl_b32 s5, s5, 2
	s_add_i32 s5, s5, s14
	s_mulk_i32 s5, 31
	s_lshr_b32 s4, s4, 2
	s_add_i32 s0, s0, s5
	s_add_i32 s34, s0, s4
	s_mul_hi_i32 s0, s34, 0x84210843
	s_add_i32 s0, s0, s34
	s_lshr_b32 s4, s0, 31
	s_ashr_i32 s0, s0, 4
	s_add_i32 s0, s0, s4
	s_mul_i32 s14, s0, 0xffffffe1
	s_add_i32 s14, s14, s34
	s_lshl_b32 s4, s14, 8
	s_lshl_b32 s15, s1, 10
	s_sub_i32 s5, 0x1f00, s4
	s_cmp_ge_i32 s15, s5
	s_cbranch_scc1 .LBB0_1246
	s_ashr_i32 s35, s34, 31
	s_lshl_b32 s11, s1, 3
	s_lshl_b64 s[34:35], s[34:35], 2
	s_add_u32 s34, s16, s34
	s_addc_u32 s35, s17, s35
	global_load_dword v110, v101, s[34:35]
	s_waitcnt vmcnt(0)
	v_readfirstlane_b32 s1, v110
	s_addk_i32 s1, 0x7f
	s_ashr_i32 s10, s1, 7
	s_cmp_ge_i32 s11, s10
	s_cbranch_scc1 .LBB0_1246
	s_ashr_i32 s1, s0, 31
	s_lshl_b64 s[38:39], s[0:1], 13
	s_ashr_i32 s5, s4, 31
	s_add_u32 s34, s38, s4
	s_addc_u32 s35, s39, s5
	s_lshl_b64 s[34:35], s[34:35], 7
	s_add_u32 s34, s26, s34
	s_addc_u32 s35, s27, s35
	s_lshl_b64 s[36:37], s[0:1], 20
	v_mov_b32_e32 v82, v196
	s_barrier
	s_add_u32 s33, s46, s36
	s_addc_u32 s36, s47, s37
	v_ashrrev_i32_e32 v64, 3, v82
	s_lshl_b64 s[4:5], s[4:5], 1
	v_lshlrev_b32_e32 v32, 4, v82
	v_add_u32_e32 v66, 32, v64
	s_add_u32 s4, s33, s4
	v_and_b32_e32 v100, 0x70, v32
	v_ashrrev_i32_e32 v65, 31, v64
	v_ashrrev_i32_e32 v67, 31, v66
	v_ashrrev_i32_e32 v80, 5, v82
	s_addc_u32 s5, s36, s5
	v_lshl_add_u64 v[24:25], s[34:35], 0, v[100:101]
	v_lshlrev_b64 v[0:1], 7, v[64:65]
	v_lshlrev_b64 v[2:3], 7, v[66:67]
	v_add_u32_e32 v68, 64, v64
	v_add_u32_e32 v70, 0x60, v64
	v_and_b32_e32 v100, 0x1f0, v32
	v_ashrrev_i32_e32 v81, 31, v80
	v_lshl_add_u64 v[0:1], v[24:25], 0, v[0:1]
	v_lshl_add_u64 v[4:5], v[24:25], 0, v[2:3]
	v_ashrrev_i32_e32 v69, 31, v68
	v_ashrrev_i32_e32 v71, 31, v70
	v_lshl_add_u64 v[32:33], s[4:5], 0, v[100:101]
	s_waitcnt lgkmcnt(0)
	v_lshlrev_b64 v[34:35], 14, v[80:81]
	global_load_dwordx4 v[0:3], v[0:1], off
	s_nop 0
	global_load_dwordx4 v[4:7], v[4:5], off
	v_lshlrev_b64 v[8:9], 7, v[68:69]
	v_lshlrev_b64 v[10:11], 7, v[70:71]
	v_add_u32_e32 v72, 0x80, v64
	v_add_u32_e32 v74, 0xa0, v64
	v_lshl_add_u64 v[60:61], v[32:33], 0, v[34:35]
	v_lshl_add_u64 v[8:9], v[24:25], 0, v[8:9]
	v_lshl_add_u64 v[12:13], v[24:25], 0, v[10:11]
	v_ashrrev_i32_e32 v73, 31, v72
	v_ashrrev_i32_e32 v75, 31, v74
	v_add_co_u32_e32 v36, vcc, s62, v60
	global_load_dwordx4 v[8:11], v[8:9], off
	s_nop 0
	global_load_dwordx4 v[12:15], v[12:13], off
	v_lshlrev_b64 v[16:17], 7, v[72:73]
	v_lshlrev_b64 v[18:19], 7, v[74:75]
	v_add_u32_e32 v76, 0xc0, v64
	v_add_u32_e32 v78, 0xe0, v64
	v_addc_co_u32_e32 v37, vcc, 0, v61, vcc
	v_lshl_add_u64 v[16:17], v[24:25], 0, v[16:17]
	v_lshl_add_u64 v[20:21], v[24:25], 0, v[18:19]
	v_ashrrev_i32_e32 v77, 31, v76
	v_ashrrev_i32_e32 v79, 31, v78
	v_add_co_u32_e32 v40, vcc, s63, v60
	global_load_dwordx4 v[16:19], v[16:17], off
	s_nop 0
	global_load_dwordx4 v[20:23], v[20:21], off
	v_lshlrev_b64 v[26:27], 7, v[76:77]
	v_lshlrev_b64 v[28:29], 7, v[78:79]
	v_addc_co_u32_e32 v41, vcc, 0, v61, vcc
	v_lshl_add_u64 v[26:27], v[24:25], 0, v[26:27]
	v_lshl_add_u64 v[28:29], v[24:25], 0, v[28:29]
	v_add_co_u32_e32 v44, vcc, s64, v60
	global_load_dwordx4 v[24:27], v[26:27], off
	s_nop 0
	global_load_dwordx4 v[28:31], v[28:29], off
	v_addc_co_u32_e32 v45, vcc, 0, v61, vcc
	v_add_co_u32_e32 v48, vcc, s65, v60
	global_load_dwordx4 v[32:35], v[60:61], off
	s_nop 0
	global_load_dwordx4 v[36:39], v[36:37], off
	v_addc_co_u32_e32 v49, vcc, 0, v61, vcc
	v_add_co_u32_e32 v52, vcc, s66, v60
	global_load_dwordx4 v[40:43], v[40:41], off
	s_nop 0
	global_load_dwordx4 v[44:47], v[44:45], off
	v_addc_co_u32_e32 v53, vcc, 0, v61, vcc
	v_add_co_u32_e32 v56, vcc, s67, v60
	global_load_dwordx4 v[48:51], v[48:49], off
	s_nop 0
	global_load_dwordx4 v[52:55], v[52:53], off
	v_addc_co_u32_e32 v57, vcc, 0, v61, vcc
	v_add_co_u32_e32 v60, vcc, s68, v60
	global_load_dwordx4 v[56:59], v[56:57], off
	s_nop 0
	v_addc_co_u32_e32 v61, vcc, 0, v61, vcc
	global_load_dwordx4 v[60:63], v[60:61], off
	v_lshrrev_b32_e32 v65, 1, v64
	v_xor_b32_e32 v65, v65, v82
	v_lshlrev_b32_e32 v65, 4, v65
	v_and_b32_e32 v65, 0x70, v65
	v_add_u32_e32 v65, 16, v65
	v_lshl_add_u32 v64, v64, 7, v65
	s_add_i32 s33, s11, 8
	s_mul_i32 s5, s0, 0x3e000
	s_mul_hi_i32 s4, s0, 0x3e000
	s_add_u32 s34, s28, s5
	s_addc_u32 s35, s29, s4
	s_not_b32 s4, s14
	s_lshl_b32 s4, s4, 7
	s_addk_i32 s4, 0x2000
	s_mul_i32 s4, s4, s14
	s_ashr_i32 s5, s4, 31
	s_lshl_b64 s[4:5], s[4:5], 1
	s_add_u32 s4, s34, s4
	s_addc_u32 s5, s35, s5
	s_or_b32 s34, s11, 1
	s_lshl_b32 s14, s34, 7
	s_waitcnt vmcnt(15)
	ds_write_b128 v64, v[0:3]
	v_lshl_add_u32 v0, v66, 7, v65
	s_waitcnt vmcnt(14)
	ds_write_b128 v0, v[4:7]
	v_lshl_add_u32 v0, v68, 7, v65
	s_min_i32 s10, s33, s10
	s_cmp_ge_i32 s34, s10
	s_cselect_b64 s[40:41], -1, 0
	s_and_b64 vcc, exec, s[40:41]
	s_waitcnt vmcnt(13)
	ds_write_b128 v0, v[8:11]
	v_lshl_add_u32 v0, v70, 7, v65
	s_waitcnt vmcnt(12)
	ds_write_b128 v0, v[12:15]
	v_lshl_add_u32 v0, v72, 7, v65
	v_add_u32_e32 v12, -1, v110
	v_add_u32_e32 v13, s15, v107
	v_add_u32_e32 v2, 0x100, v13
	v_add_u32_e32 v4, 0x180, v13
	v_add_u32_e32 v6, 0x200, v13
	v_add_u32_e32 v8, 0x280, v13
	v_add_u32_e32 v10, 0x300, v13
	v_min_i32_e32 v2, v2, v12
	v_min_i32_e32 v4, v4, v12
	s_waitcnt vmcnt(11)
	ds_write_b128 v0, v[16:19]
	v_lshl_add_u32 v0, v74, 7, v65
	s_waitcnt vmcnt(10)
	ds_write_b128 v0, v[20:23]
	v_lshl_add_u32 v0, v76, 7, v65
	v_min_i32_e32 v6, v6, v12
	v_min_i32_e32 v8, v8, v12
	v_min_i32_e32 v10, v10, v12
	v_ashrrev_i32_e32 v3, 31, v2
	v_ashrrev_i32_e32 v5, 31, v4
	s_waitcnt vmcnt(9)
	ds_write_b128 v0, v[24:27]
	v_lshl_add_u32 v0, v78, 7, v65
	s_waitcnt vmcnt(8)
	ds_write_b128 v0, v[28:31]
	v_mul_lo_u32 v0, v80, s60
	v_add3_u32 v0, 16, v100, v0
	v_add_u32_e32 v1, 0x8000, v0
	s_waitcnt vmcnt(7)
	ds_write2_b64 v1, v[32:33], v[34:35] offset1:1
	v_add_u32_e32 v1, 0x9040, v0
	s_waitcnt vmcnt(6)
	ds_write2_b64 v1, v[36:37], v[38:39] offset1:1
	v_add_u32_e32 v1, 0xa080, v0
	s_waitcnt vmcnt(5)
	ds_write2_b64 v1, v[40:41], v[42:43] offset1:1
	v_add_u32_e32 v1, 0xb0c0, v0
	s_waitcnt vmcnt(4)
	ds_write2_b64 v1, v[44:45], v[46:47] offset1:1
	v_add_u32_e32 v1, 0xc100, v0
	v_ashrrev_i32_e32 v7, 31, v6
	s_waitcnt vmcnt(3)
	ds_write2_b64 v1, v[48:49], v[50:51] offset1:1
	v_add_u32_e32 v1, 0xd140, v0
	s_waitcnt vmcnt(2)
	ds_write2_b64 v1, v[52:53], v[54:55] offset1:1
	v_add_u32_e32 v1, 0xe180, v0
	v_add_u32_e32 v0, 0xf1c0, v0
	v_ashrrev_i32_e32 v9, 31, v8
	s_waitcnt vmcnt(1)
	ds_write2_b64 v1, v[56:57], v[58:59] offset1:1
	v_ashrrev_i32_e32 v11, 31, v10
	v_lshl_add_u64 v[2:3], v[2:3], 1, s[4:5]
	s_waitcnt vmcnt(0)
	ds_write2_b64 v0, v[60:61], v[62:63] offset1:1
	v_min_i32_e32 v0, v13, v12
	v_ashrrev_i32_e32 v1, 31, v0
	v_lshl_add_u64 v[0:1], v[0:1], 1, s[4:5]
	s_waitcnt lgkmcnt(0)
	s_barrier
	global_load_ushort v100, v[0:1], off
	v_add_u32_e32 v0, s14, v107
	v_min_i32_e32 v0, v0, v12
	v_add_u32_e32 v13, 0x380, v13
	v_ashrrev_i32_e32 v1, 31, v0
	v_min_i32_e32 v12, v13, v12
	v_lshl_add_u64 v[0:1], v[0:1], 1, s[4:5]
	v_ashrrev_i32_e32 v13, 31, v12
	v_lshl_add_u64 v[4:5], v[4:5], 1, s[4:5]
	v_lshl_add_u64 v[6:7], v[6:7], 1, s[4:5]
	v_lshl_add_u64 v[8:9], v[8:9], 1, s[4:5]
	v_lshl_add_u64 v[10:11], v[10:11], 1, s[4:5]
	v_lshl_add_u64 v[12:13], v[12:13], 1, s[4:5]
	global_load_ushort v117, v[0:1], off
	global_load_ushort v116, v[2:3], off
	global_load_ushort v115, v[4:5], off
	global_load_ushort v114, v[6:7], off
	global_load_ushort v113, v[8:9], off
	global_load_ushort v112, v[10:11], off
	global_load_ushort v111, v[12:13], off
	v_mov_b32_e32 v1, s39
	s_waitcnt vmcnt(7)
	v_and_b32_e32 v118, 0x1fff, v100
	v_or_b32_e32 v0, s38, v118
	v_lshlrev_b64 v[0:1], 7, v[0:1]
	v_lshl_add_u64 v[0:1], v[102:103], 0, v[0:1]
	global_load_dwordx4 v[80:83], v[0:1], off offset:96
	global_load_dwordx4 v[84:87], v[0:1], off offset:64
	global_load_dwordx4 v[88:91], v[0:1], off offset:32
	global_load_dwordx4 v[92:95], v[0:1], off
	s_waitcnt vmcnt(3)
	v_mov_b64_e32 v[64:65], v[80:81]
	s_waitcnt vmcnt(2)
	v_mov_b64_e32 v[68:69], v[84:85]
	s_waitcnt vmcnt(1)
	v_mov_b64_e32 v[72:73], v[88:89]
	s_waitcnt vmcnt(0)
	v_mov_b64_e32 v[76:77], v[92:93]
	v_mov_b64_e32 v[66:67], v[82:83]
	v_mov_b64_e32 v[70:71], v[86:87]
	v_mov_b64_e32 v[74:75], v[90:91]
	v_mov_b64_e32 v[78:79], v[94:95]
	s_cbranch_vccnz .LBB0_1251
	v_and_b32_e32 v0, 0x1fff, v117
	v_or_b32_e32 v0, s38, v0
	v_mov_b32_e32 v1, s39
	v_lshlrev_b64 v[0:1], 7, v[0:1]
	v_lshl_add_u64 v[0:1], v[102:103], 0, v[0:1]
	global_load_dwordx4 v[76:79], v[0:1], off
	global_load_dwordx4 v[72:75], v[0:1], off offset:32
	global_load_dwordx4 v[68:71], v[0:1], off offset:64
	global_load_dwordx4 v[64:67], v[0:1], off offset:96
